# P2: pass-A-first vs GEMM-first order keyed on bx bit 3 so each XCD mixes both (on top of attention remap)
# baseline (speedup 1.0000x reference)
.LBB0_199:
	s_bitcmp0_b32 s64, 3
	s_cselect_b64 s[94:95], -1, 0
	s_cmp_lt_i32 s20, 1
	s_cselect_b64 s[2:3], -1, 0
	s_or_b64 s[2:3], s[94:95], s[2:3]
	s_mov_b32 s1, 0
	s_and_b64 vcc, exec, s[2:3]
	s_cbranch_vccnz .LBB0_222
	s_cmp_lt_i32 s64, 64
	s_cselect_b32 s0, 64, 0xffffffc0
	s_add_i32 s8, s64, s0
	s_addk_i32 s8, 0x700
	s_add_u32 s34, s90, 0x1e800000
	s_addc_u32 s35, s91, 0
	v_readlane_b32 s2, v246, 36
	s_add_u32 s56, s90, 0x1ea00000
	v_readlane_b32 s3, v246, 37
	s_addc_u32 s57, s91, 0
	s_movk_i32 s9, 0x2880
	v_mov_b64_e32 v[32:33], s[2:3]
	s_movk_i32 s10, 0x1000
	s_mov_b32 s11, 0x800000
	s_mov_b32 s16, 0x3f317217
	s_mov_b32 s17, 0x7f800000
	v_mov_b32_e32 v46, 0x41b17218
	s_movk_i32 s18, 0x7f
	s_movk_i32 s19, 0x2040
	s_add_i32 s21, 0, 0x8100
	s_movk_i32 s22, 0x480
	s_movk_i32 s23, 0x48
	v_mov_b32_e32 v35, 0
	s_movk_i32 s24, 0x90
	s_mov_b32 s25, 0
	s_mov_b32 s99, s64
	s_lshl_b32 s100, s99, 3
	s_lshl_b32 s101, s99, 6
	s_and_b32 s100, s100, 0xffffe000
	s_and_b32 s101, s101, 0x1fc0
	s_or_b32 s100, s100, s101
	s_and_b32 s98, s99, 0x380
	v_ashrrev_i32_e32 v206, 6, v210
	v_bfi_b32 v208, -4, v206, v210
	v_lshlrev_b32_e32 v208, 4, v208
	v_mov_b32_e32 v209, 0
	v_bfe_u32 v206, v210, 2, 6
	v_or_b32_e32 v206, s100, v206
	v_mad_i64_i32 v[200:201], vcc, v206, s9, v[32:33]
	s_lshl_b32 s100, s98, 1
	s_mov_b32 s101, 0
	v_lshl_add_u64 v[200:201], v[200:201], 0, s[100:101]
	v_lshl_add_u64 v[200:201], v[208:209], 1, v[200:201]
	v_add_u32_e32 v202, s98, v208
	v_mov_b32_e32 v203, 0
	v_lshl_add_u64 v[202:203], v[202:203], 2, s[54:55]
	s_movk_i32 s100, 0x1000
	v_lshl_add_u64 v[204:205], v[200:201], 0, s[100:101]
	global_load_dwordx4 v[160:163], v[200:201], off offset:2048
	global_load_dwordx4 v[164:167], v[200:201], off offset:2064
	global_load_dwordx4 v[168:171], v[202:203], off
	global_load_dwordx4 v[172:175], v[202:203], off offset:16
	global_load_dwordx4 v[176:179], v[200:201], off offset:16
	global_load_dwordx4 v[180:183], v[200:201], off
	global_load_dwordx4 v[184:187], v[204:205], off
	global_load_dwordx4 v[188:191], v[204:205], off offset:16
	global_load_dwordx4 v[192:195], v[202:203], off offset:48
	global_load_dwordx4 v[196:199], v[202:203], off offset:32
	s_waitcnt vmcnt(0)
	s_branch .LBB0_202
